# NA: row-quad rotated by 2 per round so every workgroup gets exactly one short edge unit (balance 57 vs 60 iterations)
# speedup vs baseline: 1.0031x; 1.0031x over previous
.LBB0_227:
	s_or_b64 exec, exec, s[6:7]
	s_lshr_b32 s10, s22, 1
	s_mov_b64 s[6:7], -1
	s_and_b64 vcc, exec, s[4:5]
	s_waitcnt lgkmcnt(0)
	s_barrier
	s_cbranch_vccz .LBB0_331
	s_movk_i32 s41, 0x480
	s_cmp_eq_u32 s22, 3
	s_cselect_b32 s41, 0x400, s41
	s_mov_b32 s53, 0x3e0293ee
	v_readlane_b32 s24, v253, 8
	v_readlane_b32 s25, v253, 9
	s_mul_i32 s1, s10, 0xe880
	s_add_u32 s24, s24, s1
	s_addc_u32 s25, s25, 0
	s_add_u32 s26, s92, 0x18e00000
	s_addc_u32 s27, s93, 0
	s_add_u32 s28, s92, 0x2ae00000
	s_addc_u32 s29, s93, 0
	v_readfirstlane_b32 s36, v172
	s_lshr_b32 s36, s36, 6
	s_and_b32 s37, s36, 3
	s_lshr_b32 s38, s36, 2
	s_lshl_b32 s39, s37, 3
	s_cmp_gt_u32 s37, 1
	s_cselect_b32 s1, 8, 0
	s_add_u32 s39, s39, s1
	v_and_b32_e32 v192, 15, v246
	v_lshrrev_b32_e32 v193, 4, v246
	v_lshrrev_b32_e32 v224, 4, v172
	v_and_b32_e32 v225, 15, v172
	v_lshlrev_b32_e32 v194, 15, v224
	v_lshl_add_u32 v194, v225, 4, v194
	v_add_u32_e32 v195, 0x100000, v194
	v_mul_u32_u24_e32 v196, 0x120, v224
	v_lshl_add_u32 v196, v225, 4, v196
	v_mul_u32_u24_e32 v197, 0x120, v224
	v_lshl_add_u32 v197, v225, 4, v197
	v_add_u32_e32 v197, 0x4800, v197
	v_mul_u32_u24_e32 v199, 0x120, v192
	v_lshl_add_u32 v199, v193, 4, v199
	s_mul_i32 s1, s39, 0x120
	v_add_u32_e32 v198, s1, v199
	v_lshrrev_b32_e32 v224, 2, v192
	v_lshl_add_u32 v224, v193, 2, v224
	v_mul_u32_u24_e32 v201, 0x120, v224
	v_and_b32_e32 v225, 3, v192
	v_lshl_add_u32 v201, v225, 3, v201
	v_add_u32_e32 v201, 0x4800, v201
	s_mul_i32 s1, s39, 0x120
	v_add_u32_e32 v200, s1, v201
	v_lshl_add_u32 v228, s37, 4, v192
	v_add_u32_e32 v224, -8, v228
	v_max_i32_e32 v224, 0, v224
	v_min_i32_e32 v229, 48, v224
	v_lshl_add_u32 v230, v193, 2, s39
	v_add_u32_e32 v224, 0, v230
	v_sub_u32_e32 v225, v224, v229
	v_cmp_gt_u32_e32 vcc, 16, v225
	v_sub_u32_e32 v224, v224, v228
	v_add_u32_e32 v224, 15, v224
	v_cndmask_b32_e32 v224, 31, v224, vcc
	v_lshlrev_b32_e32 v202, 2, v224
	v_add_u32_e32 v224, 1, v230
	v_sub_u32_e32 v225, v224, v229
	v_cmp_gt_u32_e32 vcc, 16, v225
	v_sub_u32_e32 v224, v224, v228
	v_add_u32_e32 v224, 15, v224
	v_cndmask_b32_e32 v224, 31, v224, vcc
	v_lshlrev_b32_e32 v203, 2, v224
	v_add_u32_e32 v224, 2, v230
	v_sub_u32_e32 v225, v224, v229
	v_cmp_gt_u32_e32 vcc, 16, v225
	v_sub_u32_e32 v224, v224, v228
	v_add_u32_e32 v224, 15, v224
	v_cndmask_b32_e32 v224, 31, v224, vcc
	v_lshlrev_b32_e32 v204, 2, v224
	v_add_u32_e32 v224, 3, v230
	v_sub_u32_e32 v225, v224, v229
	v_cmp_gt_u32_e32 vcc, 16, v225
	v_sub_u32_e32 v224, v224, v228
	v_add_u32_e32 v224, 15, v224
	v_cndmask_b32_e32 v224, 31, v224, vcc
	v_lshlrev_b32_e32 v205, 2, v224
	v_add_u32_e32 v224, 16, v230
	v_sub_u32_e32 v225, v224, v229
	v_cmp_gt_u32_e32 vcc, 16, v225
	v_sub_u32_e32 v224, v224, v228
	v_add_u32_e32 v224, 15, v224
	v_cndmask_b32_e32 v224, 31, v224, vcc
	v_lshlrev_b32_e32 v206, 2, v224
	v_add_u32_e32 v224, 17, v230
	v_sub_u32_e32 v225, v224, v229
	v_cmp_gt_u32_e32 vcc, 16, v225
	v_sub_u32_e32 v224, v224, v228
	v_add_u32_e32 v224, 15, v224
	v_cndmask_b32_e32 v224, 31, v224, vcc
	v_lshlrev_b32_e32 v207, 2, v224
	v_add_u32_e32 v224, 18, v230
	v_sub_u32_e32 v225, v224, v229
	v_cmp_gt_u32_e32 vcc, 16, v225
	v_sub_u32_e32 v224, v224, v228
	v_add_u32_e32 v224, 15, v224
	v_cndmask_b32_e32 v224, 31, v224, vcc
	v_lshlrev_b32_e32 v208, 2, v224
	v_add_u32_e32 v224, 19, v230
	v_sub_u32_e32 v225, v224, v229
	v_cmp_gt_u32_e32 vcc, 16, v225
	v_sub_u32_e32 v224, v224, v228
	v_add_u32_e32 v224, 15, v224
	v_cndmask_b32_e32 v224, 31, v224, vcc
	v_lshlrev_b32_e32 v209, 2, v224
	v_lshlrev_b32_e32 v210, 15, v192
	v_lshl_add_u32 v210, v193, 4, v210
	v_lshlrev_b32_e32 v211, 15, v192
	v_lshl_add_u32 v211, v193, 3, v211
	v_and_b32_e32 v224, 1, v193
	v_mul_u32_u24_e32 v224, 24, v224
	v_add_u32_e32 v211, v211, v224
	v_lshlrev_b32_e32 v212, 13, v192
	v_lshl_add_u32 v212, v193, 3, v212
	v_add_u32_e32 v212, v212, v224
	v_lshrrev_b32_e32 v224, 5, v172
	v_and_b32_e32 v225, 31, v172
	v_cmp_gt_u32_e32 vcc, 15, v224
	v_cmp_gt_u32_e64 s[22:23], 31, v225
	s_and_b64 s[22:23], s[22:23], vcc
	v_mul_u32_u24_e32 v224, 31, v224
	v_add_lshl_u32 v224, v224, v225, 2
	v_cndmask_b32_e64 v213, 0, v224, s[22:23]
	v_lshlrev_b32_e32 v214, 2, v172
	v_add_u32_e32 v214, 0x12000, v214
	v_xor_b32_e32 v215, 16, v246
	v_lshlrev_b32_e32 v215, 2, v215
	v_xor_b32_e32 v216, 32, v246
	v_lshlrev_b32_e32 v216, 2, v216
	v_xor_b32_e32 v217, 48, v246
	v_lshlrev_b32_e32 v217, 2, v217
	s_mov_b32 s40, s62
	s_cmp_ge_u32 s40, 0x400
	s_cbranch_scc1 .Lna_dec_ctx_0
	s_mov_b32 s45, 0
	s_cmp_eq_u32 s94, 0x100
	s_cbranch_scc0 .Lna_dec_gen_0
	s_lshr_b32 s1, s40, 8
	s_and_b32 s2, s40, 0xff
	s_lshl_b32 s1, s1, 5
	s_and_b32 s4, s2, 7
	s_lshl_b32 s4, s4, 2
	s_add_u32 s1, s1, s4
	s_lshr_b32 s4, s2, 6
	s_add_u32 s1, s1, s4
	s_bfe_u32 s44, s2, 0x30003
	s_lshr_b32 s4, s40, 7
	s_and_b32 s4, s4, 6
	s_add_u32 s44, s44, s4
	s_and_b32 s44, s44, 7
	s_branch .Lna_dec_l2_0

.Lna_nostore:
	s_waitcnt lgkmcnt(0)
	s_barrier
	s_sub_u32 s66, 0x9000, s66
	s_add_u32 s52, s52, 1
	s_cmp_lt_u32 s52, s51
	s_cbranch_scc1 .Lna_it
	global_load_dwordx4 v[128:131], v211, s[16:17] offset:0
	global_load_dwordx4 v[132:135], v211, s[16:17] offset:64
	global_load_dwordx4 v[136:139], v211, s[16:17] offset:128
	global_load_dwordx4 v[140:143], v211, s[16:17] offset:192
	s_add_u32 s15, s40, s94
	s_cmp_lt_u32 s15, s41
	s_cselect_b32 s40, s15, s40
	s_cmp_ge_u32 s40, 0x400
	s_cbranch_scc1 .Lna_dec_ctx_1
	s_mov_b32 s45, 0
	s_cmp_eq_u32 s94, 0x100
	s_cbranch_scc0 .Lna_dec_gen_1
	s_lshr_b32 s1, s40, 8
	s_and_b32 s2, s40, 0xff
	s_lshl_b32 s1, s1, 5
	s_and_b32 s4, s2, 7
	s_lshl_b32 s4, s4, 2
	s_add_u32 s1, s1, s4
	s_lshr_b32 s4, s2, 6
	s_add_u32 s1, s1, s4
	s_bfe_u32 s44, s2, 0x30003
	s_lshr_b32 s4, s40, 7
	s_and_b32 s4, s4, 6
	s_add_u32 s44, s44, s4
	s_and_b32 s44, s44, 7
	s_branch .Lna_dec_l2_1
